# P4 patch + P3 prompt item: Q~ fragments of chunk c+1 requested one chunk ahead (8 spare quads, v241-249 new), waits that only covered them dropped
# speedup vs baseline: 1.0142x; 1.0090x over previous
; #define LAS __attribute__((address_space(3)))
; #define LBAR() do { asm volatile("s_waitcnt lgkmcnt(0)" ::: "memory"); __builtin_amdgcn_s_barrier(); asm volatile("" ::: "memory"); } while (0)
; __device__ __forceinline__ void ret_prompt_item(Frame& F, int item) {
;     const int b = item >> 6, h = (item >> 3) & 7, sl = item & 7;
;     const int w = F.wave, lane = F.lane, fr = lane & 15, fq = lane >> 4, tq = (lane & 15) >> 2, tp = lane & 3;
;     const int ns = w < 4 ? w : 11 - w;
;     const float gam = 1.0f - exp2f(-5.0f - (float)h);
;     const float g127 = exp2f(127.0f * log2f(gam));
;     const bf16* Qg = WSP(bf16, WS_Q) + (size_t)(b * 2048) * D + h * DK;
;     const bf16* Kg = WSP(bf16, WS_K) + (size_t)(b * 2048) * D + h * DK;
;     const bf16* Vg = WSP(bf16, WS_V) + (size_t)(b * 2048) * HV + h * DV + sl * 64;
;     bf16* Og = WSP(bf16, WS_O) + (size_t)(b * 2048) * HV + h * DV + sl * 64;
;     LAS unsigned char* lds = F.lds;
;     f32x4 sacc[4][2];
; #pragma unroll
;     for (int a = 0; a < 4; ++a)
; #pragma unroll
;         for (int d = 0; d < 2; ++d) sacc[a][d] = (f32x4){0.f, 0.f, 0.f, 0.f};
;     u32x4 kreg[8], vreg[2];
; #pragma unroll
;     for (int i = 0; i < 8; ++i) { const int idx = F.tid + 512 * i, row = idx >> 5, c16 = idx & 31; kreg[i] = *(const u32x4*)(Kg + (size_t)row * D + 8 * c16); }
; #pragma unroll
;     for (int i = 0; i < 2; ++i) { const int idx = F.tid + 512 * i, row = idx >> 3, c16 = idx & 7; vreg[i] = *(const u32x4*)(Vg + (size_t)row * HV + 8 * c16); }
;     LBAR();
; #pragma unroll
;     for (int i = 0; i < 8; ++i) { const int idx = F.tid + 512 * i, row = idx >> 5, c16 = idx & 31; *(LAS u32x4*)(lds + KT_OFF + row * KT_ROW + c16 * 16) = kreg[i]; }
; #pragma unroll
;     for (int i = 0; i < 2; ++i) { const int idx = F.tid + 512 * i, row = idx >> 3, c16 = idx & 7; *(LAS u32x4*)(lds + VT_OFF + row * VT_ROW + c16 * 16) = vreg[i]; }
;     for (int c = 0; c < 16; ++c) {
;         const int t0 = 128 * c;
;         bf16x8 qf[8];
;         { const bf16* qp = Qg + (size_t)(t0 + 16 * ns + fr) * D + 8 * fq;
; #pragma unroll
;           for (int ks = 0; ks < 8; ++ks) qf[ks] = *(const bf16x8*)(qp + 32 * ks); }
.LBB0_623:
	s_bfe_u32 s74, s73, 0x30003
	v_cvt_f32_ubyte0_e32 v2, s74
	v_sub_f32_e32 v2, 0xc0a00000, v2
	v_cmp_gt_f32_e32 vcc, s71, v2
	s_ashr_i32 s75, s73, 6
	s_and_b64 s[22:23], vcc, exec
	v_cndmask_b32_e32 v3, 0, v192, vcc
	v_add_f32_e32 v2, v2, v3
	v_exp_f32_e32 v2, v2
	s_cselect_b32 s8, 0xffffffc0, 0
	v_mov_b32_e32 v159, v131
	v_mov_b32_e32 v161, v131
	v_ldexp_f32 v2, v2, s8
	v_sub_f32_e32 v164, 1.0, v2
	v_cmp_gt_f32_e32 vcc, s72, v164
	s_and_b64 s[22:23], vcc, exec
	s_cselect_b32 s8, 32, 0
	s_lshl_b32 s22, s75, 11
	s_ashr_i32 s23, s22, 31
	s_lshl_b64 s[78:79], s[22:23], 12
	s_add_u32 s10, s37, s78
	s_addc_u32 s52, s38, s79
	s_lshl_b32 s53, s74, 9
	s_add_u32 s80, s10, s53
	s_addc_u32 s81, s52, 0
	s_lshl_b32 s10, s73, 6
	s_and_b32 s76, s10, 0x1c0
	s_lshl_b64 s[22:23], s[22:23], 13
	s_add_u32 s10, s39, s22
	s_addc_u32 s52, s56, s23
	s_lshl_b32 s54, s74, 10
	s_add_u32 s10, s10, s54
	s_addc_u32 s52, s52, 0
	s_add_u32 s55, s58, s78
	s_addc_u32 s60, s59, s79
	s_add_u32 s22, s68, s22
	s_addc_u32 s23, s69, s23
	s_add_u32 s22, s22, s54
	s_addc_u32 s23, s23, 0
	s_lshl_b32 s54, s76, 1
	s_add_u32 s22, s22, s54
	s_addc_u32 s23, s23, 0
	v_lshl_add_u64 v[166:167], s[80:81], 0, v[130:131]
	v_lshl_add_u64 v[168:169], s[22:23], 0, v[158:159]
	v_lshl_add_u64 v[2:3], v[166:167], 0, v[132:133]
	v_lshl_add_u64 v[6:7], v[166:167], 0, v[134:135]
	v_lshl_add_u64 v[10:11], v[166:167], 0, v[136:137]
	v_lshl_add_u64 v[14:15], v[166:167], 0, v[138:139]
	v_lshl_add_u64 v[18:19], v[166:167], 0, v[140:141]
	v_lshl_add_u64 v[22:23], v[166:167], 0, v[142:143]
	v_lshl_add_u64 v[26:27], v[166:167], 0, v[144:145]
	v_lshl_add_u64 v[30:31], v[166:167], 0, v[146:147]
	v_lshl_add_u64 v[34:35], v[168:169], 0, v[148:149]
	v_lshl_add_u64 v[38:39], v[168:169], 0, v[150:151]
	global_load_dwordx4 v[2:5], v[2:3], off
	s_nop 0
	global_load_dwordx4 v[6:9], v[6:7], off
	s_nop 0
	global_load_dwordx4 v[10:13], v[10:11], off
	s_nop 0
	global_load_dwordx4 v[14:17], v[14:15], off
	s_nop 0
	global_load_dwordx4 v[18:21], v[18:19], off
	s_nop 0
	global_load_dwordx4 v[22:25], v[22:23], off
	s_nop 0
	global_load_dwordx4 v[26:29], v[26:27], off
	s_nop 0
	global_load_dwordx4 v[30:33], v[30:31], off
	s_nop 0
	global_load_dwordx4 v[34:37], v[34:35], off
	s_nop 0
	global_load_dwordx4 v[38:41], v[38:39], off
	v_ldexp_f32 v43, v164, s8
	v_log_f32_e32 v43, v43
	v_cndmask_b32_e32 v42, 0, v193, vcc
	s_add_u32 s22, s55, s53
	s_addc_u32 s23, s60, 0
	v_sub_f32_e32 v42, v43, v42
	v_mul_f32_e32 v43, 0x42fe0000, v42
	v_cmp_gt_f32_e32 vcc, s71, v43
	s_and_b64 s[78:79], vcc, exec
	s_waitcnt lgkmcnt(0)
	s_barrier
	v_cndmask_b32_e32 v43, 0, v192, vcc
	v_fmac_f32_e32 v43, 0x42fe0000, v42
	v_exp_f32_e32 v42, v43
	v_lshl_add_u64 v[172:173], s[22:23], 0, v[160:161]
	s_cselect_b32 s8, 0xffffffc0, 0
	s_add_u32 s22, s10, s54
	v_mov_b32_e32 v163, v131
	v_ldexp_f32 v174, v42, s8
	s_addc_u32 s23, s52, 0
	s_mov_b32 s77, s9
	v_lshl_add_u32 v238, s9, 7, v153
	v_mov_b32_e32 v239, 0
	v_lshlrev_b64 v[238:239], 12, v[238:239]
	v_lshl_add_u64 v[238:239], v[172:173], 0, v[238:239]
	global_load_dwordx4 v[210:213], v[238:239], off
	global_load_dwordx4 v[214:217], v[238:239], off offset:64
	global_load_dwordx4 v[222:225], v[238:239], off offset:128
	global_load_dwordx4 v[226:229], v[238:239], off offset:192
	global_load_dwordx4 v[230:233], v[238:239], off offset:256
	global_load_dwordx4 v[234:237], v[238:239], off offset:320
	global_load_dwordx4 v[242:245], v[238:239], off offset:384
	global_load_dwordx4 v[246:249], v[238:239], off offset:448
	v_mov_b32_e32 v102, 0
	v_mov_b32_e32 v103, v131
	v_mov_b32_e32 v104, 0
	v_mov_b32_e32 v105, v131
	v_mov_b32_e32 v98, 0
	v_mov_b32_e32 v99, v131
	v_mov_b32_e32 v100, 0
	v_mov_b32_e32 v101, v131
	v_mov_b32_e32 v94, 0
	v_mov_b32_e32 v95, v131
	v_mov_b32_e32 v96, 0
	v_mov_b32_e32 v97, v131
	v_mov_b32_e32 v90, 0
	v_mov_b32_e32 v91, v131
	v_mov_b32_e32 v92, 0
	v_mov_b32_e32 v170, v164
	v_mov_b32_e32 v171, v164
	v_mov_b32_e32 v176, v174
	v_mov_b32_e32 v177, v174
	v_lshl_add_u64 v[178:179], s[22:23], 0, v[162:163]
	v_mov_b32_e32 v93, v131
	v_mov_b32_e32 v86, 0
	v_mov_b32_e32 v87, v131
	v_mov_b32_e32 v88, 0
	v_mov_b32_e32 v89, v131
	v_mov_b32_e32 v78, 0
	v_mov_b32_e32 v79, v131
	v_mov_b32_e32 v80, 0
	v_mov_b32_e32 v81, v131
	v_mov_b32_e32 v82, 0
	v_mov_b32_e32 v83, v131
	v_mov_b32_e32 v84, 0
	v_mov_b32_e32 v85, v131
	v_mov_b32_e32 v74, 0
	v_mov_b32_e32 v75, v131
	v_mov_b32_e32 v76, 0
	v_mov_b32_e32 v77, v131
	s_waitcnt vmcnt(9)
	ds_write_b128 v194, v[2:5]
	s_waitcnt vmcnt(8)
	ds_write_b128 v195, v[6:9]
	s_waitcnt vmcnt(7)
	ds_write_b128 v194, v[10:13] offset:17408
	s_waitcnt vmcnt(6)
	ds_write_b128 v196, v[14:17]
	s_waitcnt vmcnt(5)
	ds_write_b128 v194, v[18:21] offset:34816
	s_waitcnt vmcnt(4)
	ds_write_b128 v197, v[22:25]
	s_waitcnt vmcnt(3)
	ds_write_b128 v194, v[26:29] offset:52224
	s_waitcnt vmcnt(2)
	ds_write_b128 v198, v[30:33]
	s_waitcnt vmcnt(1)
	ds_write_b128 v199, v[34:37]
	s_waitcnt vmcnt(0)
	ds_write_b128 v200, v[38:41]
	s_branch .LBB0_625
	s_nop 0
	s_nop 0
	s_nop 0
	s_nop 0
	s_nop 0
	s_nop 0
	s_nop 0
	s_nop 0
	s_nop 0
	s_nop 0
	s_nop 0
	s_nop 0
	s_nop 0
	s_nop 0
	s_nop 0
	s_nop 0
	s_nop 0
	s_nop 0
	s_nop 0
	s_nop 0
	s_nop 0
; #define LAS __attribute__((address_space(3)))
; __device__ __forceinline__ void ret_prompt_item(Frame& F, int item) {
;     ...
;     for (int c = 0; c < 16; ++c) {
;         const int t0 = 128 * c;
;         bf16x8 qf[8];
;         { const bf16* qp = Qg + (size_t)(t0 + 16 * ns + fr) * D + 8 * fq;
; #pragma unroll
;           for (int ks = 0; ks < 8; ++ks) qf[ks] = *(const bf16x8*)(qp + 32 * ks); }
;         LBAR();
;         { const int cn = c + 1 < 16 ? c + 1 : c; const bf16* kp = Kg + (size_t)(128 * cn) * D; const bf16* vp = Vg + (size_t)(128 * cn) * HV;
; #pragma unroll
;           for (int i = 0; i < 8; ++i) { const int idx = F.tid + 512 * i, row = idx >> 5, c16 = idx & 31; kreg[i] = *(const u32x4*)(kp + (size_t)row * D + 8 * c16); }
; #pragma unroll
;           for (int i = 0; i < 2; ++i) { const int idx = F.tid + 512 * i, row = idx >> 3, c16 = idx & 7; vreg[i] = *(const u32x4*)(vp + (size_t)row * HV + 8 * c16); } }
; #pragma unroll
;         for (int a = 0; a < 4; ++a)
; #pragma unroll
;             for (int d = 0; d < 2; ++d) sacc[a][d] *= gam;
; #pragma unroll
;         for (int ks = 0; ks < 4; ++ks) {
;             bf16x8 bk[2];
; #pragma unroll
;             for (int dt = 0; dt < 2; ++dt) { const LAS unsigned char* p = lds + KT_OFF + (32 * ks + 4 * fq + tq) * KT_ROW + (32 * w + 16 * dt + 4 * tp) * 2; bk[dt] = cat8(tr16(p), tr16(p + 16 * KT_ROW)); }
;     ...
;         { bf16* op = Og + (size_t)(t0 + 16 * ns + fr) * HV + 4 * fq;
; #pragma unroll
;           for (int et = 0; et < 4; ++et) { u32x2 o2; o2.x = pk2(oacc[et][0], oacc[et][1]); o2.y = pk2(oacc[et][2], oacc[et][3]); *(u32x2*)(op + 16 * et) = o2; } }
;         LBAR();
; #pragma unroll
;         for (int et = 0; et < 4; ++et)
; #pragma unroll
;             for (int dt = 0; dt < 2; ++dt) { u32x2 o2; o2.x = pk2(sacc[et][dt][0], sacc[et][dt][1]); o2.y = pk2(sacc[et][dt][2], sacc[et][dt][3]);
;                 *(LAS u32x2*)(lds + SD_OFF + (32 * w + 16 * dt + fr) * SD_ROW + (16 * et + 4 * fq) * 2) = o2; }
; #pragma unroll
;         for (int i = 0; i < 8; ++i) { const int idx = F.tid + 512 * i, row = idx >> 5, c16 = idx & 31; *(LAS u32x4*)(lds + KT_OFF + row * KT_ROW + c16 * 16) = kreg[i]; }
; #pragma unroll
;         for (int i = 0; i < 2; ++i) { const int idx = F.tid + 512 * i, row = idx >> 3, c16 = idx & 7; *(LAS u32x4*)(lds + VT_OFF + row * VT_ROW + c16 * 16) = vreg[i]; }
.LBB0_624:
	s_nop 0
	v_lshlrev_b64 v[2:3], 13, v[180:181]
	v_lshl_add_u64 v[2:3], v[178:179], 0, v[2:3]
	v_cvt_pk_bf16_f32 v4, v106, v107
	v_cvt_pk_bf16_f32 v5, v108, v109
	global_store_dwordx2 v[2:3], v[4:5], off
	v_cvt_pk_bf16_f32 v4, v110, v111
	v_cvt_pk_bf16_f32 v5, v112, v113
	v_mov_b32_e32 v175, v174
	global_store_dwordx2 v[2:3], v[4:5], off offset:32
	v_cvt_pk_bf16_f32 v4, v114, v115
	v_cvt_pk_bf16_f32 v5, v116, v117
	v_pk_mul_f32 v[104:105], v[174:175], v[104:105]
	v_pk_mul_f32 v[102:103], v[176:177], v[102:103]
	global_store_dwordx2 v[2:3], v[4:5], off offset:64
	v_cvt_pk_bf16_f32 v4, v118, v119
	v_cvt_pk_bf16_f32 v5, v120, v121
	global_store_dwordx2 v[2:3], v[4:5], off offset:96
	v_cvt_pk_bf16_f32 v2, v102, v103
	v_cvt_pk_bf16_f32 v3, v104, v105
	v_pk_mul_f32 v[96:97], v[174:175], v[96:97]
	v_pk_mul_f32 v[94:95], v[176:177], v[94:95]
	v_pk_mul_f32 v[92:93], v[174:175], v[92:93]
	v_pk_mul_f32 v[90:91], v[176:177], v[90:91]
	s_waitcnt lgkmcnt(0)
	s_barrier
	s_waitcnt vmcnt(20)
	v_cvt_pk_bf16_f32 v6, v94, v95
	v_cvt_pk_bf16_f32 v7, v96, v97
	ds_write2_b64 v191, v[2:3], v[6:7] offset1:4
	v_cvt_pk_bf16_f32 v2, v90, v91
	v_cvt_pk_bf16_f32 v3, v92, v93
	v_add_u32_e32 v8, 0x800, v191
	v_pk_mul_f32 v[100:101], v[174:175], v[100:101]
	v_pk_mul_f32 v[98:99], v[176:177], v[98:99]
	v_pk_mul_f32 v[88:89], v[174:175], v[88:89]
	v_pk_mul_f32 v[86:87], v[176:177], v[86:87]
	v_cvt_pk_bf16_f32 v4, v98, v99
	v_cvt_pk_bf16_f32 v5, v100, v101
	ds_write2_b64 v8, v[4:5], v[2:3] offset0:64 offset1:68
	v_cvt_pk_bf16_f32 v2, v86, v87
	v_cvt_pk_bf16_f32 v3, v88, v89
	v_pk_mul_f32 v[80:81], v[174:175], v[80:81]
	v_pk_mul_f32 v[78:79], v[176:177], v[78:79]
	v_pk_mul_f32 v[84:85], v[174:175], v[84:85]
	v_pk_mul_f32 v[82:83], v[176:177], v[82:83]
	v_pk_mul_f32 v[76:77], v[174:175], v[76:77]
	v_pk_mul_f32 v[74:75], v[176:177], v[74:75]
	v_cvt_pk_bf16_f32 v4, v78, v79
	v_cvt_pk_bf16_f32 v5, v80, v81
	v_cvt_pk_bf16_f32 v6, v82, v83
	v_cvt_pk_bf16_f32 v7, v84, v85
	ds_write2_b64 v191, v[2:3], v[6:7] offset0:8 offset1:12
	v_cvt_pk_bf16_f32 v2, v74, v75
	v_cvt_pk_bf16_f32 v3, v76, v77
	s_cmp_eq_u32 s77, 16
	ds_write2_b64 v8, v[4:5], v[2:3] offset0:72 offset1:76
	s_waitcnt vmcnt(13)
	ds_write_b128 v194, v[34:37]
	s_waitcnt vmcnt(12)
	ds_write_b128 v195, v[38:41]
	s_waitcnt vmcnt(11)
	ds_write_b128 v194, v[42:45] offset:17408
	s_waitcnt vmcnt(10)
	ds_write_b128 v196, v[46:49]
	s_waitcnt vmcnt(9)
	ds_write_b128 v194, v[50:53] offset:34816
	s_waitcnt vmcnt(8)
	ds_write_b128 v197, v[54:57]
	s_waitcnt vmcnt(7)
	ds_write_b128 v194, v[58:61] offset:52224
	s_waitcnt vmcnt(6)
	ds_write_b128 v198, v[62:65]
	s_waitcnt vmcnt(5)
	ds_write_b128 v199, v[70:73]
	s_waitcnt vmcnt(4)
	ds_write_b128 v200, v[66:69]
	s_cbranch_scc1 .LBB0_622
.LBB0_625:
	s_mov_b32 s10, s77
	v_lshl_add_u32 v180, s10, 7, v153
	v_ashrrev_i32_e32 v181, 31, v180
	s_add_i32 s94, s77, 1
	s_min_u32 s94, s94, 15
	v_lshl_add_u32 v238, s94, 7, v153
	v_mov_b32_e32 v239, 0
	v_mov_b64_e32 v[2:3], v[210:211]
	v_mov_b64_e32 v[4:5], v[212:213]
	v_mov_b64_e32 v[6:7], v[214:215]
	v_mov_b64_e32 v[8:9], v[216:217]
	v_mov_b64_e32 v[10:11], v[222:223]
	v_mov_b64_e32 v[12:13], v[224:225]
	v_mov_b64_e32 v[14:15], v[226:227]
	v_mov_b64_e32 v[16:17], v[228:229]
	v_mov_b64_e32 v[18:19], v[230:231]
	v_mov_b64_e32 v[20:21], v[232:233]
	v_mov_b64_e32 v[22:23], v[234:235]
	v_mov_b64_e32 v[24:25], v[236:237]
	v_mov_b64_e32 v[26:27], v[242:243]
	v_mov_b64_e32 v[28:29], v[244:245]
	v_mov_b64_e32 v[30:31], v[246:247]
	v_mov_b64_e32 v[32:33], v[248:249]
	v_lshlrev_b64 v[238:239], 12, v[238:239]
	v_lshl_add_u64 v[238:239], v[172:173], 0, v[238:239]
	global_load_dwordx4 v[210:213], v[238:239], off
	global_load_dwordx4 v[214:217], v[238:239], off offset:64
	global_load_dwordx4 v[222:225], v[238:239], off offset:128
	global_load_dwordx4 v[226:229], v[238:239], off offset:192
	global_load_dwordx4 v[230:233], v[238:239], off offset:256
	global_load_dwordx4 v[234:237], v[238:239], off offset:320
	global_load_dwordx4 v[242:245], v[238:239], off offset:384
	global_load_dwordx4 v[246:249], v[238:239], off offset:448
	s_waitcnt lgkmcnt(0)
	s_barrier
	v_mov_b32_e32 v165, v164
	ds_read_b64_tr_b16 v[40:41], v190 offset:2560
	ds_read_b64_tr_b16 v[38:39], v190
	ds_read_b64_tr_b16 v[44:45], v189 offset:8704
	ds_read_b64_tr_b16 v[42:43], v189
	ds_read_b64_tr_b16 v[48:49], v189 offset:8736
	ds_read_b64_tr_b16 v[46:47], v189 offset:32
	ds_read_b64_tr_b16 v[50:51], v190 offset:32
	ds_read_b64_tr_b16 v[54:55], v190 offset:64
	ds_read_b64_tr_b16 v[58:59], v190 offset:96
	ds_read_b64_tr_b16 v[52:53], v190 offset:2592
	ds_read_b64_tr_b16 v[56:57], v190 offset:2624
	ds_read_b64_tr_b16 v[60:61], v190 offset:2656
	v_pk_mul_f32 v[36:37], v[164:165], v[104:105]
	v_pk_mul_f32 v[34:35], v[170:171], v[102:103]
	v_pk_mul_f32 v[64:65], v[164:165], v[100:101]
	v_pk_mul_f32 v[62:63], v[170:171], v[98:99]
	s_waitcnt lgkmcnt(8)
	v_mfma_f32_16x16x32_bf16 v[34:37], v[38:41], v[42:45], v[34:37]
	v_mul_f32_e64 v68, v164, v92
	v_mul_f32_e64 v69, v165, v93
	v_pk_mul_f32 v[66:67], v[170:171], v[90:91]
	v_pk_mul_f32 v[72:73], v[164:165], v[80:81]
	s_waitcnt lgkmcnt(6)
	v_mfma_f32_16x16x32_bf16 v[38:41], v[38:41], v[46:49], v[62:65]
	v_mul_f32_e64 v70, v170, v78
	v_mul_f32_e64 v71, v171, v79
	s_add_i32 s77, s77, 1
	s_lshl_b32 s8, s77, 7
	v_pk_mul_f32 v[64:65], v[164:165], v[96:97]
	v_pk_mul_f32 v[62:63], v[170:171], v[94:95]
	s_cmp_lg_u32 s10, 15
	s_cselect_b32 s8, s8, 0x780
	s_waitcnt lgkmcnt(2)
; #define LAS __attribute__((address_space(3)))
; __device__ __forceinline__ s16x4 tr16(const LAS unsigned char* p) { return __builtin_bit_cast(s16x4, __builtin_amdgcn_ds_read_tr16_b64_v4i16((LAS v4i16_t*)p)); }
; __device__ __forceinline__ bf16x8 cat8(s16x4 lo, s16x4 hi) { return __builtin_shufflevector(lo, hi, 0, 1, 2, 3, 4, 5, 6, 7); }
; __device__ __forceinline__ void ret_prompt_item(Frame& F, int item) {
;     ...
;         { const int cn = c + 1 < 16 ? c + 1 : c; const bf16* kp = Kg + (size_t)(128 * cn) * D; const bf16* vp = Vg + (size_t)(128 * cn) * HV;
; #pragma unroll
;           for (int i = 0; i < 8; ++i) { const int idx = F.tid + 512 * i, row = idx >> 5, c16 = idx & 31; kreg[i] = *(const u32x4*)(kp + (size_t)row * D + 8 * c16); }
; #pragma unroll
;           for (int i = 0; i < 2; ++i) { const int idx = F.tid + 512 * i, row = idx >> 3, c16 = idx & 7; vreg[i] = *(const u32x4*)(vp + (size_t)row * HV + 8 * c16); } }
; #pragma unroll
;         for (int a = 0; a < 4; ++a)
; #pragma unroll
;             for (int d = 0; d < 2; ++d) sacc[a][d] *= gam;
; #pragma unroll
;         for (int ks = 0; ks < 4; ++ks) {
;             bf16x8 bk[2];
; #pragma unroll
;             for (int dt = 0; dt < 2; ++dt) { const LAS unsigned char* p = lds + KT_OFF + (32 * ks + 4 * fq + tq) * KT_ROW + (32 * w + 16 * dt + 4 * tp) * 2; bk[dt] = cat8(tr16(p), tr16(p + 16 * KT_ROW)); }
; #pragma unroll
;             for (int et = 0; et < 4; ++et) {
;                 const LAS unsigned char* p = lds + VT_OFF + (32 * ks + 4 * fq + tq) * VT_ROW + (16 * et + 4 * tp) * 2;
;                 const bf16x8 a = cat8(tr16(p), tr16(p + 16 * VT_ROW));
; #pragma unroll
;                 for (int dt = 0; dt < 2; ++dt) sacc[et][dt] = __builtin_amdgcn_mfma_f32_16x16x32_bf16(a, bk[dt], sacc[et][dt], 0, 0, 0);
;             }
;         }
	v_mfma_f32_16x16x32_bf16 v[62:65], v[50:53], v[42:45], v[62:65]
	s_lshl_b64 s[22:23], s[8:9], 12
	v_lshl_add_u64 v[114:115], v[166:167], 0, s[22:23]
	s_lshl_b64 s[78:79], s[8:9], 13
	v_mfma_f32_16x16x32_bf16 v[50:53], v[50:53], v[46:49], v[66:69]
	s_cmp_eq_u32 s10, 0
	s_nop 1
	v_pk_mul_f32 v[68:69], v[164:165], v[88:89]
	v_pk_mul_f32 v[66:67], v[170:171], v[86:87]
	s_waitcnt lgkmcnt(1)
	s_nop 0
	v_mfma_f32_16x16x32_bf16 v[66:69], v[54:57], v[42:45], v[66:69]
	v_mfma_f32_16x16x32_bf16 v[54:57], v[54:57], v[46:49], v[70:73]
	s_nop 2
	v_mul_f32_e64 v72, v164, v84
	v_mul_f32_e64 v73, v165, v85
	v_pk_mul_f32 v[70:71], v[170:171], v[82:83]
	s_waitcnt lgkmcnt(0)
	s_nop 0
	v_mfma_f32_16x16x32_bf16 v[42:45], v[58:61], v[42:45], v[70:73]
	s_nop 2
	v_mul_f32_e64 v72, v164, v76
	v_mul_f32_e64 v73, v165, v77
	v_pk_mul_f32 v[70:71], v[170:171], v[74:75]
	s_nop 1
	v_mfma_f32_16x16x32_bf16 v[46:49], v[58:61], v[46:49], v[70:73]
	ds_read_b64_tr_b16 v[58:59], v190 offset:5120
	ds_read_b64_tr_b16 v[60:61], v190 offset:7680
	s_nop 0
	ds_read_b64_tr_b16 v[70:71], v189 offset:17408
	ds_read_b64_tr_b16 v[72:73], v189 offset:26112
	ds_read_b64_tr_b16 v[76:77], v189 offset:26144
	ds_read_b64_tr_b16 v[74:75], v189 offset:17440
	ds_read_b64_tr_b16 v[78:79], v190 offset:5152
	ds_read_b64_tr_b16 v[82:83], v190 offset:5184
	ds_read_b64_tr_b16 v[86:87], v190 offset:5216
	ds_read_b64_tr_b16 v[80:81], v190 offset:7712
	ds_read_b64_tr_b16 v[84:85], v190 offset:7744
	ds_read_b64_tr_b16 v[88:89], v190 offset:7776
	s_waitcnt lgkmcnt(8)
	v_mfma_f32_16x16x32_bf16 v[34:37], v[58:61], v[70:73], v[34:37]
	s_waitcnt lgkmcnt(6)
	v_mfma_f32_16x16x32_bf16 v[38:41], v[58:61], v[74:77], v[38:41]
	s_waitcnt lgkmcnt(2)
	v_mfma_f32_16x16x32_bf16 v[58:61], v[78:81], v[70:73], v[62:65]
	v_mfma_f32_16x16x32_bf16 v[50:53], v[78:81], v[74:77], v[50:53]
	s_waitcnt lgkmcnt(1)
	v_mfma_f32_16x16x32_bf16 v[62:65], v[82:85], v[70:73], v[66:69]
	v_mfma_f32_16x16x32_bf16 v[54:57], v[82:85], v[74:77], v[54:57]
	s_waitcnt lgkmcnt(0)
	v_mfma_f32_16x16x32_bf16 v[42:45], v[86:89], v[70:73], v[42:45]
	v_mfma_f32_16x16x32_bf16 v[46:49], v[86:89], v[74:77], v[46:49]
	ds_read_b64_tr_b16 v[66:67], v190 offset:10240
	ds_read_b64_tr_b16 v[68:69], v190 offset:12800
	ds_read_b64_tr_b16 v[70:71], v189 offset:34816
	ds_read_b64_tr_b16 v[72:73], v189 offset:43520
	ds_read_b64_tr_b16 v[76:77], v189 offset:43552
	ds_read_b64_tr_b16 v[74:75], v189 offset:34848
	ds_read_b64_tr_b16 v[78:79], v190 offset:10272
	ds_read_b64_tr_b16 v[82:83], v190 offset:10304
	ds_read_b64_tr_b16 v[86:87], v190 offset:10336
	ds_read_b64_tr_b16 v[80:81], v190 offset:12832
	ds_read_b64_tr_b16 v[84:85], v190 offset:12864
	ds_read_b64_tr_b16 v[88:89], v190 offset:12896
	s_waitcnt lgkmcnt(8)
	v_mfma_f32_16x16x32_bf16 v[34:37], v[66:69], v[70:73], v[34:37]
	s_waitcnt lgkmcnt(6)
	v_mfma_f32_16x16x32_bf16 v[38:41], v[66:69], v[74:77], v[38:41]
	s_waitcnt lgkmcnt(2)
	v_mfma_f32_16x16x32_bf16 v[58:61], v[78:81], v[70:73], v[58:61]
	v_mfma_f32_16x16x32_bf16 v[50:53], v[78:81], v[74:77], v[50:53]
	s_waitcnt lgkmcnt(1)
	v_mfma_f32_16x16x32_bf16 v[62:65], v[82:85], v[70:73], v[62:65]
	v_mfma_f32_16x16x32_bf16 v[66:69], v[82:85], v[74:77], v[54:57]
	s_waitcnt lgkmcnt(0)
	v_mfma_f32_16x16x32_bf16 v[70:73], v[86:89], v[70:73], v[42:45]
	s_nop 2
	ds_read_b64_tr_b16 v[42:43], v190 offset:15360
	ds_read_b64_tr_b16 v[44:45], v190 offset:17920
	ds_read_b64_tr_b16 v[82:83], v189 offset:52224
	ds_read_b64_tr_b16 v[84:85], v189 offset:60928
	ds_read_b64_tr_b16 v[108:109], v189 offset:60960
	ds_read_b64_tr_b16 v[106:107], v189 offset:52256
	ds_read_b64_tr_b16 v[54:55], v190 offset:15392
	ds_read_b64_tr_b16 v[78:79], v190 offset:15424
	ds_read_b64_tr_b16 v[110:111], v190 offset:15456
	ds_read_b64_tr_b16 v[56:57], v190 offset:17952
	ds_read_b64_tr_b16 v[80:81], v190 offset:17984
	ds_read_b64_tr_b16 v[112:113], v190 offset:18016
	v_mfma_f32_16x16x32_bf16 v[74:77], v[86:89], v[74:77], v[46:49]
	s_waitcnt lgkmcnt(8)
	v_mfma_f32_16x16x32_bf16 v[102:105], v[42:45], v[82:85], v[34:37]
	s_nop 0
	v_lshl_add_u64 v[46:47], v[114:115], 0, v[134:135]
	s_nop 0
	v_lshl_add_u64 v[34:35], v[114:115], 0, v[132:133]
	s_waitcnt lgkmcnt(6)
	v_mfma_f32_16x16x32_bf16 v[98:101], v[42:45], v[106:109], v[38:41]
	global_load_dwordx4 v[34:37], v[34:35], off
	s_nop 1
	global_load_dwordx4 v[38:41], v[46:47], off
	v_lshl_add_u64 v[42:43], v[114:115], 0, v[136:137]
	v_lshl_add_u64 v[46:47], v[114:115], 0, v[138:139]
	s_waitcnt lgkmcnt(2)
	v_mfma_f32_16x16x32_bf16 v[94:97], v[54:57], v[82:85], v[58:61]
	global_load_dwordx4 v[42:45], v[42:43], off
	s_nop 0
	global_load_dwordx4 v[46:49], v[46:47], off
	v_lshl_add_u64 v[58:59], v[114:115], 0, v[140:141]
	v_lshl_add_u64 v[60:61], v[114:115], 0, v[142:143]
	s_waitcnt lgkmcnt(1)
	v_mfma_f32_16x16x32_bf16 v[86:89], v[78:81], v[82:85], v[62:65]
	v_mfma_f32_16x16x32_bf16 v[78:81], v[78:81], v[106:109], v[66:69]
	s_nop 1
	v_lshl_add_u64 v[62:63], v[114:115], 0, v[146:147]
	v_lshl_add_u64 v[66:67], v[168:169], 0, s[78:79]
	v_mfma_f32_16x16x32_bf16 v[90:93], v[54:57], v[106:109], v[50:53]
	s_nop 2
	global_load_dwordx4 v[50:53], v[58:59], off
	global_load_dwordx4 v[54:57], v[60:61], off
	v_lshl_add_u64 v[58:59], v[114:115], 0, v[144:145]
	v_lshl_add_u64 v[68:69], v[66:67], 0, v[148:149]
	v_lshl_add_u64 v[66:67], v[66:67], 0, v[150:151]
	global_load_dwordx4 v[58:61], v[58:59], off
	s_nop 0
	global_load_dwordx4 v[62:65], v[62:63], off
	s_waitcnt lgkmcnt(0)
	v_mfma_f32_16x16x32_bf16 v[82:85], v[110:113], v[82:85], v[70:73]
	s_nop 2
	global_load_dwordx4 v[70:73], v[68:69], off
	s_nop 0
	global_load_dwordx4 v[66:69], v[66:67], off
	v_mfma_f32_16x16x32_bf16 v[74:77], v[110:113], v[106:109], v[74:77]
	s_cbranch_scc1 .LBB0_627
; #define LAS __attribute__((address_space(3)))
; __device__ __forceinline__ s16x4 tr16(const LAS unsigned char* p) { return __builtin_bit_cast(s16x4, __builtin_amdgcn_ds_read_tr16_b64_v4i16((LAS v4i16_t*)p)); }
; __device__ __forceinline__ bf16x8 cat8(s16x4 lo, s16x4 hi) { return __builtin_shufflevector(lo, hi, 0, 1, 2, 3, 4, 5, 6, 7); }
; __device__ __forceinline__ void ret_prompt_item(Frame& F, int item) {
;     ...
;         if (c > 0) {
; #pragma unroll
;             for (int ks = 0; ks < 8; ++ks)
; #pragma unroll
;                 for (int et = 0; et < 4; ++et) {
;                     const LAS unsigned char* p = lds + SD_OFF + (32 * ks + 8 * fq + tq) * SD_ROW + (16 * et + 4 * tp) * 2;
;                     const bf16x8 a = cat8(tr16(p), tr16(p + 4 * SD_ROW));
;                     oacc[et] = __builtin_amdgcn_mfma_f32_16x16x32_bf16(a, qf[ks], oacc[et], 0, 0, 0);
;                 }
; #pragma unroll
;             for (int et = 0; et < 4; ++et) oacc[et] *= gam;
;         }
	ds_read_b64_tr_b16 v[106:107], v186
	ds_read_b64_tr_b16 v[108:109], v186 offset:640
	ds_read_b64_tr_b16 v[112:113], v186 offset:672
	ds_read_b64_tr_b16 v[110:111], v186 offset:32
	ds_read_b64_tr_b16 v[114:115], v186 offset:64
	ds_read_b64_tr_b16 v[118:119], v186 offset:96
	ds_read_b64_tr_b16 v[116:117], v186 offset:704
	ds_read_b64_tr_b16 v[120:121], v186 offset:736
	ds_read_b64_tr_b16 v[122:123], v186 offset:5120
	ds_read_b64_tr_b16 v[124:125], v186 offset:5760
	ds_read_b64_tr_b16 v[128:129], v186 offset:5792
	ds_read_b64_tr_b16 v[126:127], v186 offset:5152
	ds_read_b64_tr_b16 v[202:203], v186 offset:5184
	ds_read_b64_tr_b16 v[206:207], v186 offset:5216
	ds_read_b64_tr_b16 v[204:205], v186 offset:5824
	ds_read_b64_tr_b16 v[208:209], v186 offset:5856
	s_waitcnt lgkmcnt(14)
	v_mfma_f32_16x16x32_bf16 v[106:109], v[106:109], v[2:5], 0
	s_waitcnt lgkmcnt(12)
	v_mfma_f32_16x16x32_bf16 v[110:113], v[110:113], v[2:5], 0
	s_waitcnt lgkmcnt(9)
	v_mfma_f32_16x16x32_bf16 v[114:117], v[114:117], v[2:5], 0
	s_waitcnt lgkmcnt(8)
	v_mfma_f32_16x16x32_bf16 v[118:121], v[118:121], v[2:5], 0
	s_waitcnt lgkmcnt(6)
	v_mfma_f32_16x16x32_bf16 v[106:109], v[122:125], v[6:9], v[106:109]
	ds_read_b64_tr_b16 v[122:123], v186 offset:10240
	ds_read_b64_tr_b16 v[124:125], v186 offset:10880
	s_waitcnt lgkmcnt(6)
	v_mfma_f32_16x16x32_bf16 v[110:113], v[126:129], v[6:9], v[110:113]
	s_waitcnt lgkmcnt(3)
	v_mfma_f32_16x16x32_bf16 v[114:117], v[202:205], v[6:9], v[114:117]
	s_waitcnt lgkmcnt(2)
	v_mfma_f32_16x16x32_bf16 v[118:121], v[206:209], v[6:9], v[118:121]
	ds_read_b64_tr_b16 v[128:129], v186 offset:10912
	ds_read_b64_tr_b16 v[126:127], v186 offset:10272
	ds_read_b64_tr_b16 v[202:203], v186 offset:10304
	ds_read_b64_tr_b16 v[206:207], v186 offset:10336
	ds_read_b64_tr_b16 v[204:205], v186 offset:10944
	ds_read_b64_tr_b16 v[208:209], v186 offset:10976
	s_waitcnt lgkmcnt(6)
	v_mfma_f32_16x16x32_bf16 v[106:109], v[122:125], v[10:13], v[106:109]
	ds_read_b64_tr_b16 v[122:123], v186 offset:15360
	ds_read_b64_tr_b16 v[124:125], v186 offset:16000
	s_waitcnt lgkmcnt(6)
	v_mfma_f32_16x16x32_bf16 v[110:113], v[126:129], v[10:13], v[110:113]
	s_waitcnt lgkmcnt(3)
	v_mfma_f32_16x16x32_bf16 v[114:117], v[202:205], v[10:13], v[114:117]
	s_waitcnt lgkmcnt(2)
	v_mfma_f32_16x16x32_bf16 v[118:121], v[206:209], v[10:13], v[118:121]
	ds_read_b64_tr_b16 v[128:129], v186 offset:16032
	ds_read_b64_tr_b16 v[126:127], v186 offset:15392
	ds_read_b64_tr_b16 v[202:203], v186 offset:15424
	ds_read_b64_tr_b16 v[206:207], v186 offset:15456
	ds_read_b64_tr_b16 v[204:205], v186 offset:16064
	ds_read_b64_tr_b16 v[208:209], v186 offset:16096
	s_waitcnt lgkmcnt(6)
	v_mfma_f32_16x16x32_bf16 v[106:109], v[122:125], v[14:17], v[106:109]
	ds_read_b64_tr_b16 v[122:123], v186 offset:20480
	ds_read_b64_tr_b16 v[124:125], v186 offset:21120
	s_waitcnt lgkmcnt(6)
	v_mfma_f32_16x16x32_bf16 v[110:113], v[126:129], v[14:17], v[110:113]
	s_waitcnt lgkmcnt(3)
	v_mfma_f32_16x16x32_bf16 v[114:117], v[202:205], v[14:17], v[114:117]
	s_waitcnt lgkmcnt(2)
	v_mfma_f32_16x16x32_bf16 v[118:121], v[206:209], v[14:17], v[118:121]
	ds_read_b64_tr_b16 v[128:129], v186 offset:21152
	ds_read_b64_tr_b16 v[126:127], v186 offset:20512
	ds_read_b64_tr_b16 v[202:203], v186 offset:20544
	ds_read_b64_tr_b16 v[206:207], v186 offset:20576
	ds_read_b64_tr_b16 v[204:205], v186 offset:21184
	ds_read_b64_tr_b16 v[208:209], v186 offset:21216
	s_waitcnt lgkmcnt(6)
	v_mfma_f32_16x16x32_bf16 v[106:109], v[122:125], v[18:21], v[106:109]
	ds_read_b64_tr_b16 v[122:123], v186 offset:25600
	ds_read_b64_tr_b16 v[124:125], v186 offset:26240
	s_waitcnt lgkmcnt(6)
	v_mfma_f32_16x16x32_bf16 v[110:113], v[126:129], v[18:21], v[110:113]
	s_waitcnt lgkmcnt(3)
	v_mfma_f32_16x16x32_bf16 v[114:117], v[202:205], v[18:21], v[114:117]
	s_waitcnt lgkmcnt(2)
	v_mfma_f32_16x16x32_bf16 v[118:121], v[206:209], v[18:21], v[118:121]
	ds_read_b64_tr_b16 v[128:129], v186 offset:26272
	ds_read_b64_tr_b16 v[126:127], v186 offset:25632
	ds_read_b64_tr_b16 v[202:203], v186 offset:25664
	ds_read_b64_tr_b16 v[206:207], v186 offset:25696
	ds_read_b64_tr_b16 v[204:205], v186 offset:26304
	ds_read_b64_tr_b16 v[208:209], v186 offset:26336
	s_waitcnt lgkmcnt(6)
	v_mfma_f32_16x16x32_bf16 v[106:109], v[122:125], v[22:25], v[106:109]
	ds_read_b64_tr_b16 v[122:123], v186 offset:30720
	ds_read_b64_tr_b16 v[124:125], v186 offset:31360
	s_waitcnt lgkmcnt(6)
	v_mfma_f32_16x16x32_bf16 v[110:113], v[126:129], v[22:25], v[110:113]
	s_waitcnt lgkmcnt(3)
	v_mfma_f32_16x16x32_bf16 v[114:117], v[202:205], v[22:25], v[114:117]
	s_waitcnt lgkmcnt(2)
	v_mfma_f32_16x16x32_bf16 v[118:121], v[206:209], v[22:25], v[118:121]
	ds_read_b64_tr_b16 v[128:129], v186 offset:31392
	ds_read_b64_tr_b16 v[126:127], v186 offset:30752
	ds_read_b64_tr_b16 v[202:203], v186 offset:30784
	ds_read_b64_tr_b16 v[206:207], v186 offset:30816
	ds_read_b64_tr_b16 v[204:205], v186 offset:31424
	ds_read_b64_tr_b16 v[208:209], v186 offset:31456
	s_waitcnt lgkmcnt(6)
	v_mfma_f32_16x16x32_bf16 v[106:109], v[122:125], v[26:29], v[106:109]
	s_waitcnt lgkmcnt(4)
	v_mfma_f32_16x16x32_bf16 v[110:113], v[126:129], v[26:29], v[110:113]
	ds_read_b64_tr_b16 v[122:123], v186 offset:35840
	ds_read_b64_tr_b16 v[124:125], v186 offset:36480
	ds_read_b64_tr_b16 v[128:129], v186 offset:36512
	s_waitcnt lgkmcnt(4)
	v_mfma_f32_16x16x32_bf16 v[114:117], v[202:205], v[26:29], v[114:117]
	s_waitcnt lgkmcnt(3)
	v_mfma_f32_16x16x32_bf16 v[118:121], v[206:209], v[26:29], v[118:121]
	ds_read_b64_tr_b16 v[126:127], v186 offset:35872
	ds_read_b64_tr_b16 v[202:203], v186 offset:35904
	ds_read_b64_tr_b16 v[206:207], v186 offset:35936
	ds_read_b64_tr_b16 v[204:205], v186 offset:36544
	ds_read_b64_tr_b16 v[208:209], v186 offset:36576
	s_waitcnt lgkmcnt(6)
	v_mfma_f32_16x16x32_bf16 v[106:109], v[122:125], v[30:33], v[106:109]
	s_waitcnt lgkmcnt(4)
	v_mfma_f32_16x16x32_bf16 v[110:113], v[126:129], v[30:33], v[110:113]
	s_waitcnt lgkmcnt(1)
	v_mfma_f32_16x16x32_bf16 v[114:117], v[202:205], v[30:33], v[114:117]
	s_nop 3
	v_mul_f32_e64 v108, v164, v108
	v_mul_f32_e64 v109, v165, v109
	v_pk_mul_f32 v[106:107], v[170:171], v[106:107]
	v_pk_mul_f32 v[112:113], v[164:165], v[112:113]
	s_waitcnt lgkmcnt(0)
	v_mfma_f32_16x16x32_bf16 v[118:121], v[206:209], v[30:33], v[118:121]
	v_mul_f32_e64 v110, v170, v110
	v_mul_f32_e64 v111, v171, v111
	v_pk_mul_f32 v[116:117], v[164:165], v[116:117]
	v_pk_mul_f32 v[114:115], v[170:171], v[114:115]
	s_nop 3
	v_pk_mul_f32 v[120:121], v[164:165], v[120:121]
	v_pk_mul_f32 v[118:119], v[170:171], v[118:119]
	s_andn2_b64 vcc, exec, s[20:21]
	s_cbranch_vccnz .LBB0_624
	s_branch .LBB0_628

; #define LAS __attribute__((address_space(3)))
; __device__ __forceinline__ void ret_prompt_item(Frame& F, int item) {
;     ...
;         for (int u2 = 0; 2 * u2 <= ns; ++u2) {
;             const int mt0 = 2 * u2, mt1 = 2 * u2 + 1;
;             f32x4 st0 = (f32x4){0.f, 0.f, 0.f, 0.f}, st1 = st0;
;             { const LAS unsigned char* ka = lds + KT_OFF + (16 * mt0 + fr) * KT_ROW + 16 * fq;
; #pragma unroll
;               for (int ks = 0; ks < 8; ++ks) { const bf16x8 a = *(const LAS bf16x8*)(ka + 64 * ks); st0 = __builtin_amdgcn_mfma_f32_16x16x32_bf16(a, qf[ks], st0, 0, 0, 0); } }
;             if (mt1 <= ns) { const LAS unsigned char* ka = lds + KT_OFF + (16 * mt1 + fr) * KT_ROW + 16 * fq;
; #pragma unroll
;               for (int ks = 0; ks < 8; ++ks) { const bf16x8 a = *(const LAS bf16x8*)(ka + 64 * ks); st1 = __builtin_amdgcn_mfma_f32_16x16x32_bf16(a, qf[ks], st1, 0, 0, 0); } }
.LBB0_630:
	v_add_u32_e32 v163, 0, v161
	ds_read_b128 v[122:125], v163
	ds_read_b128 v[126:129], v163 offset:64
	ds_read_b128 v[202:205], v163 offset:128
	s_cmp_ge_i32 s8, s57
	s_cselect_b64 s[22:23], -1, 0
	s_waitcnt lgkmcnt(2)
	v_mfma_f32_16x16x32_bf16 v[122:125], v[122:125], v[2:5], 0
	s_and_b64 vcc, exec, s[22:23]
	ds_read_b128 v[206:209], v163 offset:448
	s_waitcnt lgkmcnt(2)
	v_mfma_f32_16x16x32_bf16 v[122:125], v[126:129], v[6:9], v[122:125]
	ds_read_b128 v[126:129], v163 offset:192
	s_waitcnt lgkmcnt(2)
	v_mfma_f32_16x16x32_bf16 v[122:125], v[202:205], v[10:13], v[122:125]
	ds_read_b128 v[202:205], v163 offset:256
	s_waitcnt lgkmcnt(1)
	v_mfma_f32_16x16x32_bf16 v[122:125], v[126:129], v[14:17], v[122:125]
	ds_read_b128 v[126:129], v163 offset:320
	s_waitcnt lgkmcnt(1)
	v_mfma_f32_16x16x32_bf16 v[122:125], v[202:205], v[18:21], v[122:125]
	ds_read_b128 v[202:205], v163 offset:384
	s_waitcnt lgkmcnt(1)
	v_mfma_f32_16x16x32_bf16 v[122:125], v[126:129], v[22:25], v[122:125]
	v_mov_b32_e32 v126, 0
	v_mov_b32_e32 v127, 0
	v_mov_b32_e32 v128, 0
	s_waitcnt lgkmcnt(0)
	v_mfma_f32_16x16x32_bf16 v[122:125], v[202:205], v[26:29], v[122:125]
	v_mov_b32_e32 v129, 0
	s_nop 0
	v_mfma_f32_16x16x32_bf16 v[122:125], v[206:209], v[30:33], v[122:125]
	s_cbranch_vccnz .LBB0_629
	ds_read_b128 v[126:129], v163 offset:8704
	ds_read_b128 v[202:205], v163 offset:8768
	ds_read_b128 v[206:209], v163 offset:8832
	s_waitcnt lgkmcnt(2)
	v_mfma_f32_16x16x32_bf16 v[126:129], v[126:129], v[2:5], 0
	s_waitcnt lgkmcnt(1)
	v_mfma_f32_16x16x32_bf16 v[126:129], v[202:205], v[6:9], v[126:129]
	ds_read_b128 v[202:205], v163 offset:8896
	s_waitcnt lgkmcnt(1)
	v_mfma_f32_16x16x32_bf16 v[126:129], v[206:209], v[10:13], v[126:129]
	ds_read_b128 v[206:209], v163 offset:8960
	s_waitcnt lgkmcnt(1)
	v_mfma_f32_16x16x32_bf16 v[126:129], v[202:205], v[14:17], v[126:129]
	ds_read_b128 v[202:205], v163 offset:9024
	s_waitcnt lgkmcnt(1)
	v_mfma_f32_16x16x32_bf16 v[126:129], v[206:209], v[18:21], v[126:129]
	ds_read_b128 v[206:209], v163 offset:9088
	s_waitcnt lgkmcnt(1)
	v_mfma_f32_16x16x32_bf16 v[126:129], v[202:205], v[22:25], v[126:129]
	ds_read_b128 v[202:205], v163 offset:9152
	s_waitcnt lgkmcnt(1)
	v_mfma_f32_16x16x32_bf16 v[126:129], v[206:209], v[26:29], v[126:129]
	s_waitcnt lgkmcnt(0)
	v_mfma_f32_16x16x32_bf16 v[126:129], v[202:205], v[30:33], v[126:129]
	s_branch .LBB0_629

; __global__ void __launch_bounds__(NTHREADS, 2) mk_fwd(Args args) {
;     extern __shared__ __attribute__((aligned(16))) unsigned char lds_raw[];
	.amdhsa_kernel _ZN2mk6mk_fwdENS_4ArgsE
		.amdhsa_group_segment_fixed_size 0
		.amdhsa_private_segment_fixed_size 0
		.amdhsa_kernarg_size 432
		.amdhsa_user_sgpr_count 2
		.amdhsa_user_sgpr_dispatch_ptr 0
		.amdhsa_user_sgpr_queue_ptr 0
		.amdhsa_user_sgpr_kernarg_segment_ptr 1
		.amdhsa_user_sgpr_dispatch_id 0
		.amdhsa_user_sgpr_kernarg_preload_length 0
		.amdhsa_user_sgpr_kernarg_preload_offset 0
		.amdhsa_user_sgpr_private_segment_size 0
		.amdhsa_uses_dynamic_stack 0
		.amdhsa_enable_private_segment 0
		.amdhsa_system_sgpr_workgroup_id_x 1
		.amdhsa_system_sgpr_workgroup_id_y 0
		.amdhsa_system_sgpr_workgroup_id_z 0
		.amdhsa_system_sgpr_workgroup_info 0
		.amdhsa_system_vgpr_workitem_id 0
		.amdhsa_next_free_vgpr 256
		.amdhsa_next_free_sgpr 98
		.amdhsa_accum_offset 256
		.amdhsa_reserve_vcc 1
		.amdhsa_float_round_mode_32 0
		.amdhsa_float_round_mode_16_64 0
		.amdhsa_float_denorm_mode_32 3
		.amdhsa_float_denorm_mode_16_64 3
		.amdhsa_dx10_clamp 1
		.amdhsa_ieee_mode 1
		.amdhsa_fp16_overflow 0
		.amdhsa_tg_split 0
		.amdhsa_exception_fp_ieee_invalid_op 0
		.amdhsa_exception_fp_denorm_src 0
		.amdhsa_exception_fp_ieee_div_zero 0
		.amdhsa_exception_fp_ieee_overflow 0
		.amdhsa_exception_fp_ieee_underflow 0
		.amdhsa_exception_fp_ieee_inexact 0
		.amdhsa_exception_int_div_zero 0
	.end_amdhsa_kernel

; __global__ void __launch_bounds__(NTHREADS, 2) mk_fwd(Args args) {
;     extern __shared__ __attribute__((aligned(16))) unsigned char lds_raw[];
.Lfunc_end0:
	.size	_ZN2mk6mk_fwdENS_4ArgsE, .Lfunc_end0-_ZN2mk6mk_fwdENS_4ArgsE
	.set _ZN2mk6mk_fwdENS_4ArgsE.num_vgpr, 256
	.set _ZN2mk6mk_fwdENS_4ArgsE.num_agpr, 0
	.set _ZN2mk6mk_fwdENS_4ArgsE.numbered_sgpr, 98
	.set _ZN2mk6mk_fwdENS_4ArgsE.num_named_barrier, 0
	.set _ZN2mk6mk_fwdENS_4ArgsE.private_seg_size, 0
	.set _ZN2mk6mk_fwdENS_4ArgsE.uses_vcc, 1
	.set _ZN2mk6mk_fwdENS_4ArgsE.uses_flat_scratch, 0
	.set _ZN2mk6mk_fwdENS_4ArgsE.has_dyn_sized_stack, 0
	.set _ZN2mk6mk_fwdENS_4ArgsE.has_recursion, 0
	.set _ZN2mk6mk_fwdENS_4ArgsE.has_indirect_call, 0

; __global__ void __launch_bounds__(NTHREADS, 2) mk_fwd(Args args) {
;     extern __shared__ __attribute__((aligned(16))) unsigned char lds_raw[];
amdhsa.kernels:
  - .agpr_count:     0
    .args:
      - .offset:         0
        .size:           176
        .value_kind:     by_value
      - .offset:         176
        .size:           4
        .value_kind:     hidden_block_count_x
      - .offset:         180
        .size:           4
        .value_kind:     hidden_block_count_y
      - .offset:         184
        .size:           4
        .value_kind:     hidden_block_count_z
      - .offset:         188
        .size:           2
        .value_kind:     hidden_group_size_x
      - .offset:         190
        .size:           2
        .value_kind:     hidden_group_size_y
      - .offset:         192
        .size:           2
        .value_kind:     hidden_group_size_z
      - .offset:         194
        .size:           2
        .value_kind:     hidden_remainder_x
      - .offset:         196
        .size:           2
        .value_kind:     hidden_remainder_y
      - .offset:         198
        .size:           2
        .value_kind:     hidden_remainder_z
      - .offset:         216
        .size:           8
        .value_kind:     hidden_global_offset_x
      - .offset:         224
        .size:           8
        .value_kind:     hidden_global_offset_y
      - .offset:         232
        .size:           8
        .value_kind:     hidden_global_offset_z
      - .offset:         240
        .size:           2
        .value_kind:     hidden_grid_dims
      - .offset:         296
        .size:           4
        .value_kind:     hidden_dynamic_lds_size
    .group_segment_fixed_size: 0
    .kernarg_segment_align: 8
    .kernarg_segment_size: 432
    .language:       OpenCL C
    .language_version:
      - 2
      - 0
    .max_flat_workgroup_size: 512
    .name:           _ZN2mk6mk_fwdENS_4ArgsE
    .private_segment_fixed_size: 0
    .sgpr_count:     104
    .sgpr_spill_count: 59
    .symbol:         _ZN2mk6mk_fwdENS_4ArgsE.kd
    .uniform_work_group_size: 1
    .uses_dynamic_stack: false
    .vgpr_count:     256
    .vgpr_spill_count: 0
    .wavefront_size: 64
